# hconv: 64-lane sum-of-squares all-reduce via DPP + permlane16/32 swaps instead of six ds_bpermute round trips
# speedup vs baseline: 1.0004x; 1.0004x over previous
.LBB0_283:
	global_load_dwordx4 v[26:29], v10, s[20:21]
	global_load_dwordx4 v[30:33], v10, s[20:21] offset:1024
	global_load_dwordx4 v[6:9], v10, s[20:21] offset:2048
	global_load_dwordx4 v[2:5], v10, s[20:21] offset:3072
	s_min_i32 s4, s12, 0x4000
	s_ashr_i32 s4, s4, 12
	s_mul_i32 s20, s4, 0xc00
	s_ashr_i32 s21, s20, 31
	s_lshl_b64 s[20:21], s[20:21], 2
	s_add_u32 s20, s2, s20
	s_addc_u32 s21, s3, s21
	v_lshl_add_u64 v[46:47], s[20:21], 0, v[10:11]
	v_add_co_u32_e32 v16, vcc, s17, v46
	s_lshl_b64 s[0:1], s[0:1], 11
	s_nop 0
	v_addc_co_u32_e32 v17, vcc, 0, v47, vcc
	global_load_dwordx4 v[34:37], v[16:17], off
	global_load_dwordx4 v[38:41], v10, s[20:21]
	global_load_dwordx4 v[42:45], v[12:13], off
	v_lshl_add_u64 v[46:47], v[46:47], 0, s[18:19]
	global_load_dwordx4 v[54:57], v[12:13], off offset:1024
	global_load_dwordx4 v[58:61], v[46:47], off offset:1024
	global_load_dwordx4 v[62:65], v10, s[20:21] offset:1024
	global_load_dwordx4 v[66:69], v[12:13], off offset:2048
	global_load_dwordx4 v[70:73], v[46:47], off offset:2048
	global_load_dwordx4 v[74:77], v10, s[20:21] offset:2048
	global_load_dwordx4 v[78:81], v[12:13], off offset:3072
	global_load_dwordx4 v[82:85], v[46:47], off offset:3072
	global_load_dwordx4 v[86:89], v10, s[20:21] offset:3072
	s_add_u32 s12, s12, s14
	s_addc_u32 s13, s13, s15
	s_add_u32 s6, s6, s8
	s_addc_u32 s7, s7, s9
	s_cmpk_lt_i32 s12, 0x4400
	s_waitcnt vmcnt(15)
	v_mul_f32_e32 v16, v27, v27
	v_mul_f32_e32 v17, v29, v29
	s_waitcnt vmcnt(14)
	v_mul_f32_e32 v25, v31, v31
	v_mul_f32_e32 v48, v33, v33
	s_waitcnt vmcnt(13)
	v_mul_f32_e32 v49, v7, v7
	v_mul_f32_e32 v50, v9, v9
	v_fmac_f32_e32 v16, v26, v26
	v_fmac_f32_e32 v17, v28, v28
	v_fmac_f32_e32 v25, v30, v30
	v_fmac_f32_e32 v48, v32, v32
	s_waitcnt vmcnt(12)
	v_mul_f32_e32 v51, v3, v3
	v_mul_f32_e32 v52, v5, v5
	v_fmac_f32_e32 v49, v6, v6
	v_fmac_f32_e32 v50, v8, v8
	v_add_f32_e32 v16, v16, v17
	v_add_f32_e32 v17, v25, v48
	v_fmac_f32_e32 v51, v2, v2
	v_fmac_f32_e32 v52, v4, v4
	v_add_f32_e32 v25, v49, v50
	v_add_f32_e32 v16, v16, v17
	v_add_f32_e32 v48, v51, v52
	v_add_f32_e32 v16, v16, v25
	v_add_f32_e32 v16, v16, v48
	s_nop 1
	v_add_f32_dpp v16, v16, v16 quad_perm:[1,0,3,2] row_mask:0xf bank_mask:0xf
	s_nop 1
	v_add_f32_dpp v16, v16, v16 quad_perm:[2,3,0,1] row_mask:0xf bank_mask:0xf
	s_nop 1
	v_add_f32_dpp v16, v16, v16 row_half_mirror row_mask:0xf bank_mask:0xf
	s_nop 1
	v_add_f32_dpp v16, v16, v16 row_mirror row_mask:0xf bank_mask:0xf
	v_mov_b32_e32 v17, v16
	s_nop 1
	v_permlane16_swap_b32_e32 v16, v17
	v_add_f32_e32 v16, v16, v17
	v_mov_b32_e32 v17, v16
	s_nop 1
	v_permlane32_swap_b32_e32 v16, v17
	v_add_f32_e32 v25, v16, v17
	s_waitcnt vmcnt(11)
	v_add_f32_e32 v34, 1.0, v34
	v_add_f32_e32 v36, 1.0, v36
	v_add_f32_e32 v35, 1.0, v35
	v_add_f32_e32 v37, 1.0, v37
	v_lshl_add_u64 v[16:17], v[14:15], 0, s[0:1]
	v_fmamk_f32 v25, v25, 0x3a800000, v23
	v_mul_f32_e32 v48, 0x4f800000, v25
	v_cmp_gt_f32_e32 vcc, s16, v25
	s_nop 1
	v_cndmask_b32_e32 v25, v25, v48, vcc
	v_sqrt_f32_e32 v48, v25
	s_nop 0
	v_add_u32_e32 v49, -1, v48
	v_add_u32_e32 v50, 1, v48
	v_fma_f32 v51, -v49, v48, v25
	v_fma_f32 v52, -v50, v48, v25
	v_cmp_ge_f32_e64 s[0:1], 0, v51
	s_nop 1
	v_cndmask_b32_e64 v48, v48, v49, s[0:1]
	v_cmp_lt_f32_e64 s[0:1], 0, v52
	s_nop 1
	v_cndmask_b32_e64 v48, v48, v50, s[0:1]
	v_mul_f32_e32 v49, 0x37800000, v48
	v_cndmask_b32_e32 v48, v48, v49, vcc
	v_cmp_class_f32_e32 vcc, v25, v24
	s_nop 1
	v_cndmask_b32_e32 v25, v48, v25, vcc
	v_div_scale_f32 v48, s[0:1], v25, v25, 1.0
	v_rcp_f32_e32 v49, v48
	v_div_scale_f32 v50, vcc, 1.0, v25, 1.0
	v_fma_f32 v51, -v48, v49, 1.0
	v_fmac_f32_e32 v49, v51, v49
	v_mul_f32_e32 v51, v50, v49
	v_fma_f32 v52, -v48, v51, v50
	v_fmac_f32_e32 v51, v52, v49
	v_fma_f32 v48, -v48, v51, v50
	v_div_fmas_f32 v48, v48, v49, v51
	v_div_fixup_f32 v25, v48, v25, 1.0
	v_mul_f32_e32 v26, v26, v25
	v_mul_f32_e32 v28, v28, v25
	v_mul_f32_e32 v27, v27, v25
	v_mul_f32_e32 v29, v29, v25
	s_waitcnt vmcnt(9)
	v_mul_f32_e32 v26, v42, v26
	v_mul_f32_e32 v28, v44, v28
	v_mul_f32_e32 v27, v43, v27
	v_mul_f32_e32 v29, v45, v29
	v_fma_f32 v26, v34, v26, v38
	v_fma_f32 v28, v36, v28, v40
	v_fma_f32 v27, v35, v27, v39
	v_fmac_f32_e32 v41, v37, v29
	v_bfe_u32 v29, v26, 16, 1
	v_bfe_u32 v35, v28, 16, 1
	v_bfe_u32 v34, v27, 16, 1
	v_bfe_u32 v36, v41, 16, 1
	v_add3_u32 v26, v26, v29, s22
	v_add3_u32 v28, v28, v35, s22
	v_add3_u32 v27, v27, v34, s22
	v_add3_u32 v29, v41, v36, s22
	v_lshrrev_b32_e32 v26, 16, v26
	v_lshrrev_b32_e32 v28, 16, v28
	v_and_or_b32 v26, v27, s23, v26
	v_and_or_b32 v27, v29, s23, v28
	global_store_dwordx2 v[16:17], v[26:27], off
	v_mul_f32_e32 v30, v30, v25
	v_mul_f32_e32 v32, v32, v25
	v_mul_f32_e32 v31, v31, v25
	v_mul_f32_e32 v33, v33, v25
	v_mul_f32_e32 v6, v6, v25
	v_mul_f32_e32 v8, v8, v25
	v_mul_f32_e32 v7, v7, v25
	v_mul_f32_e32 v9, v9, v25
	v_mul_f32_e32 v2, v2, v25
	v_mul_f32_e32 v4, v4, v25
	v_mul_f32_e32 v3, v3, v25
	v_mul_f32_e32 v5, v5, v25
	s_waitcnt vmcnt(7)
	v_mul_f32_e32 v26, v54, v30
	v_add_f32_e32 v30, 1.0, v58
	v_mul_f32_e32 v28, v56, v32
	v_add_f32_e32 v32, 1.0, v60
	v_mul_f32_e32 v27, v55, v31
	v_add_f32_e32 v31, 1.0, v59
	v_mul_f32_e32 v29, v57, v33
	v_add_f32_e32 v33, 1.0, v61
	v_fma_f32 v26, v30, v26, v62
	v_fma_f32 v28, v32, v28, v64
	v_fma_f32 v27, v31, v27, v63
	v_fma_f32 v41, v33, v29, v65
	v_bfe_u32 v29, v26, 16, 1
	v_bfe_u32 v31, v28, 16, 1
	v_bfe_u32 v30, v27, 16, 1
	v_bfe_u32 v32, v41, 16, 1
	v_add3_u32 v26, v26, v29, s22
	v_add3_u32 v28, v28, v31, s22
	v_add3_u32 v27, v27, v30, s22
	v_add3_u32 v29, v41, v32, s22
	v_lshrrev_b32_e32 v26, 16, v26
	v_lshrrev_b32_e32 v28, 16, v28
	v_and_or_b32 v26, v27, s23, v26
	v_and_or_b32 v27, v29, s23, v28
	global_store_dwordx2 v[16:17], v[26:27], off offset:512
	s_waitcnt vmcnt(5)
	v_mul_f32_e32 v6, v66, v6
	v_add_f32_e32 v26, 1.0, v70
	v_mul_f32_e32 v8, v68, v8
	v_add_f32_e32 v28, 1.0, v72
	v_mul_f32_e32 v7, v67, v7
	v_add_f32_e32 v27, 1.0, v71
	v_mul_f32_e32 v9, v69, v9
	v_add_f32_e32 v29, 1.0, v73
	v_fma_f32 v6, v6, v26, v74
	v_fma_f32 v8, v8, v28, v76
	v_fma_f32 v7, v7, v27, v75
	v_fma_f32 v37, v9, v29, v77
	v_bfe_u32 v9, v6, 16, 1
	v_bfe_u32 v27, v8, 16, 1
	v_bfe_u32 v26, v7, 16, 1
	v_bfe_u32 v28, v37, 16, 1
	v_add3_u32 v6, v6, v9, s22
	v_add3_u32 v8, v8, v27, s22
	v_add3_u32 v7, v7, v26, s22
	v_add3_u32 v9, v37, v28, s22
	v_lshrrev_b32_e32 v6, 16, v6
	v_lshrrev_b32_e32 v8, 16, v8
	v_and_or_b32 v6, v7, s23, v6
	v_and_or_b32 v7, v9, s23, v8
	global_store_dwordx2 v[16:17], v[6:7], off offset:1024
	s_waitcnt vmcnt(3)
	v_mul_f32_e32 v2, v2, v78
	v_add_f32_e32 v6, 1.0, v82
	v_mul_f32_e32 v4, v4, v80
	v_add_f32_e32 v8, 1.0, v84
	v_mul_f32_e32 v3, v3, v79
	v_add_f32_e32 v7, 1.0, v83
	v_mul_f32_e32 v5, v5, v81
	v_add_f32_e32 v9, 1.0, v85
	v_fma_f32 v2, v2, v6, v86
	v_fma_f32 v4, v4, v8, v88
	v_fma_f32 v3, v3, v7, v87
	v_fma_f32 v33, v5, v9, v89
	v_bfe_u32 v5, v2, 16, 1
	v_bfe_u32 v7, v4, 16, 1
	v_bfe_u32 v6, v3, 16, 1
	v_bfe_u32 v8, v33, 16, 1
	v_add3_u32 v2, v2, v5, s22
	v_add3_u32 v4, v4, v7, s22
	v_add3_u32 v3, v3, v6, s22
	v_add3_u32 v5, v33, v8, s22
	v_lshrrev_b32_e32 v2, 16, v2
	v_lshrrev_b32_e32 v4, 16, v4
	v_and_or_b32 v2, v3, s23, v2
	v_and_or_b32 v3, v5, s23, v4
	global_store_dwordx2 v[16:17], v[2:3], off offset:1536
	s_cbranch_scc0 .LBB0_286
